# rmsnorm 4-row loop (post-wout and post-ffn-down instances): the 8 gain-vector loads hoisted ahead of the reduction, removing the vmcnt(0) between store groups
# speedup vs baseline: 1.0012x; 1.0001x over previous
; __device__ __forceinline__ const float* lin(const Params& P, int k) { return P.in[k] + lzero(); }
; DI void phase_rmsnorm(LAS unsigned char* lds_, const Params& P, const float* gain, int mode, int fix, int nch) {
;     ...
;     for (; row + 3 * stride < MPR; row += 4 * stride) {
;         f32x4 v4[4][8]; float s4[4];
; #pragma unroll
;         for (int u = 0; u < 4; ++u) { const int r = row + u * stride; const float* sp = (mode == 1) ? lin(P, 0) + (size_t)r * DM : H + (size_t)r * DM;
; #pragma unroll
;             for (int i = 0; i < 8; ++i) v4[u][i] = *(const f32x4*)(sp + i * 256 + lane * 4); }
; #pragma unroll
;         for (int u = 0; u < 4; ++u) { float s = 0.f;
; #pragma unroll
;             for (int i = 0; i < 8; ++i) s += v4[u][i][0] * v4[u][i][0] + v4[u][i][1] * v4[u][i][1] + v4[u][i][2] * v4[u][i][2] + v4[u][i][3] * v4[u][i][3];
;             s4[u] = rsqrtf(wsum(s) * (1.f / DM) + 1e-6f); }
; #pragma unroll
;         for (int i = 0; i < 8; ++i) { const f32x4 g = *(const f32x4*)(gain + i * 256 + lane * 4);
.LBB0_1880:
	v_lshl_add_u64 v[2:3], s[92:93], 0, v[152:153]
	global_load_dwordx4 v[114:117], v[2:3], off
	global_load_dwordx4 v[98:101], v[2:3], off offset:1024
	global_load_dwordx4 v[82:85], v[2:3], off offset:2048
	global_load_dwordx4 v[66:69], v[2:3], off offset:3072
	v_add_co_u32_e32 v2, vcc, 0x1000, v2
	v_lshl_add_u64 v[6:7], s[92:93], 0, v[158:159]
	s_nop 0
	v_addc_co_u32_e32 v3, vcc, 0, v3, vcc
	global_load_dwordx4 v[50:53], v[2:3], off
	global_load_dwordx4 v[34:37], v[2:3], off offset:1024
	global_load_dwordx4 v[14:17], v[2:3], off offset:2048
	s_nop 0
	global_load_dwordx4 v[2:5], v[2:3], off offset:3072
	s_nop 0
	global_load_dwordx4 v[122:125], v[6:7], off
	global_load_dwordx4 v[102:105], v[6:7], off offset:1024
	global_load_dwordx4 v[86:89], v[6:7], off offset:2048
	global_load_dwordx4 v[70:73], v[6:7], off offset:3072
	v_add_co_u32_e32 v6, vcc, 0x1000, v6
	v_add_u32_e32 v166, s4, v130
	s_nop 0
	v_addc_co_u32_e32 v7, vcc, 0, v7, vcc
	global_load_dwordx4 v[54:57], v[6:7], off
	global_load_dwordx4 v[38:41], v[6:7], off offset:1024
	global_load_dwordx4 v[22:25], v[6:7], off offset:2048
	s_nop 0
	global_load_dwordx4 v[6:9], v[6:7], off offset:3072
	v_ashrrev_i32_e32 v167, 31, v166
	v_lshlrev_b64 v[10:11], 13, v[166:167]
	v_lshl_add_u64 v[10:11], v[148:149], 0, v[10:11]
	global_load_dwordx4 v[126:129], v[10:11], off
	global_load_dwordx4 v[106:109], v[10:11], off offset:1024
	global_load_dwordx4 v[90:93], v[10:11], off offset:2048
	global_load_dwordx4 v[74:77], v[10:11], off offset:3072
	v_add_co_u32_e32 v10, vcc, s88, v10
	v_add_u32_e32 v168, s5, v130
	s_nop 0
	v_addc_co_u32_e32 v11, vcc, 0, v11, vcc
	global_load_dwordx4 v[58:61], v[10:11], off
	global_load_dwordx4 v[42:45], v[10:11], off offset:1024
	global_load_dwordx4 v[26:29], v[10:11], off offset:2048
	s_nop 0
	global_load_dwordx4 v[10:13], v[10:11], off offset:3072
	v_ashrrev_i32_e32 v169, 31, v168
	v_lshlrev_b64 v[18:19], 13, v[168:169]
	v_lshl_add_u64 v[18:19], v[148:149], 0, v[18:19]
	global_load_dwordx4 v[118:121], v[18:19], off
	global_load_dwordx4 v[110:113], v[18:19], off offset:1024
	global_load_dwordx4 v[94:97], v[18:19], off offset:2048
	global_load_dwordx4 v[78:81], v[18:19], off offset:3072
	v_add_co_u32_e32 v18, vcc, s88, v18
	v_add_u32_e32 v130, s6, v130
	s_nop 0
	v_addc_co_u32_e32 v19, vcc, 0, v19, vcc
	global_load_dwordx4 v[62:65], v[18:19], off
	global_load_dwordx4 v[46:49], v[18:19], off offset:1024
	global_load_dwordx4 v[30:33], v[18:19], off offset:2048
	s_nop 0
	global_load_dwordx4 v[18:21], v[18:19], off offset:3072
	v_lshl_add_u64 v[152:153], v[152:153], 0, s[8:9]
	v_lshl_add_u64 v[158:159], v[158:159], 0, s[8:9]
	global_load_dwordx4 v[206:209], v[138:139], off
	global_load_dwordx4 v[210:213], v[138:139], off offset:1024
	global_load_dwordx4 v[214:217], v[138:139], off offset:2048
	global_load_dwordx4 v[218:221], v[138:139], off offset:3072
	global_load_dwordx4 v[222:225], v[140:141], off
	global_load_dwordx4 v[226:229], v[142:143], off
	global_load_dwordx4 v[230:233], v[144:145], off
	global_load_dwordx4 v[188:191], v[146:147], off
	s_waitcnt vmcnt(31)
	v_mov_b32_e32 v181, v115
	s_waitcnt vmcnt(30)
	v_mov_b32_e32 v183, v99
	s_waitcnt vmcnt(27)
	v_mov_b32_e32 v174, v51
	s_waitcnt vmcnt(26)
	v_mov_b32_e32 v175, v35
	v_mov_b32_e32 v160, v50
	v_mov_b32_e32 v161, v34
	v_pk_mul_f32 v[174:175], v[174:175], v[174:175]
	s_waitcnt vmcnt(25)
	v_mov_b32_e32 v176, v15
	v_pk_fma_f32 v[160:161], v[160:161], v[160:161], v[174:175]
	v_mov_b32_e32 v174, v52
	v_mov_b32_e32 v175, v36
	v_pk_fma_f32 v[160:161], v[174:175], v[174:175], v[160:161]
	v_mov_b32_e32 v174, v53
	v_mov_b32_e32 v175, v37
	s_waitcnt vmcnt(24)
	v_mov_b32_e32 v177, v3
	v_pk_fma_f32 v[160:161], v[174:175], v[174:175], v[160:161]
	v_mov_b32_e32 v174, v14
	v_mov_b32_e32 v175, v2
	v_pk_mul_f32 v[176:177], v[176:177], v[176:177]
	s_waitcnt vmcnt(19)
	v_mov_b32_e32 v178, v55
	v_pk_fma_f32 v[174:175], v[174:175], v[174:175], v[176:177]
	v_mov_b32_e32 v176, v16
	v_mov_b32_e32 v177, v4
	v_pk_fma_f32 v[174:175], v[176:177], v[176:177], v[174:175]
	v_mov_b32_e32 v176, v17
	v_mov_b32_e32 v177, v5
	s_waitcnt vmcnt(18)
	v_mov_b32_e32 v179, v39
	v_pk_fma_f32 v[174:175], v[176:177], v[176:177], v[174:175]
	v_mov_b32_e32 v176, v54
	v_mov_b32_e32 v177, v38
	v_pk_mul_f32 v[178:179], v[178:179], v[178:179]
	v_mov_b32_e32 v180, v123
	v_pk_fma_f32 v[176:177], v[176:177], v[176:177], v[178:179]
	v_mov_b32_e32 v178, v56
	v_mov_b32_e32 v179, v40
	v_pk_fma_f32 v[176:177], v[178:179], v[178:179], v[176:177]
	v_mov_b32_e32 v178, v57
	v_mov_b32_e32 v179, v41
	v_pk_fma_f32 v[176:177], v[178:179], v[178:179], v[176:177]
	v_mov_b32_e32 v178, v122
	v_mov_b32_e32 v179, v114
	v_pk_mul_f32 v[180:181], v[180:181], v[180:181]
	v_mov_b32_e32 v182, v103
	v_pk_fma_f32 v[178:179], v[178:179], v[178:179], v[180:181]
	v_mov_b32_e32 v180, v124
	v_mov_b32_e32 v181, v116
	v_pk_fma_f32 v[178:179], v[180:181], v[180:181], v[178:179]
	v_mov_b32_e32 v180, v125
	v_mov_b32_e32 v181, v117
	v_pk_fma_f32 v[178:179], v[180:181], v[180:181], v[178:179]
	v_mov_b32_e32 v180, v102
	v_mov_b32_e32 v181, v98
	v_pk_mul_f32 v[182:183], v[182:183], v[182:183]
	s_waitcnt vmcnt(7)
; DI void phase_rmsnorm(LAS unsigned char* lds_, const Params& P, const float* gain, int mode, int fix, int nch) {
;     ...
;         for (int u = 0; u < 4; ++u) { float s = 0.f;
; #pragma unroll
;             for (int i = 0; i < 8; ++i) s += v4[u][i][0] * v4[u][i][0] + v4[u][i][1] * v4[u][i][1] + v4[u][i][2] * v4[u][i][2] + v4[u][i][3] * v4[u][i][3];
;             s4[u] = rsqrtf(wsum(s) * (1.f / DM) + 1e-6f); }
	v_mov_b32_e32 v184, v119
	v_pk_fma_f32 v[180:181], v[180:181], v[180:181], v[182:183]
	v_mov_b32_e32 v182, v104
	v_mov_b32_e32 v183, v100
	v_pk_fma_f32 v[180:181], v[182:183], v[182:183], v[180:181]
	v_mov_b32_e32 v182, v105
	v_mov_b32_e32 v183, v101
	v_pk_fma_f32 v[180:181], v[182:183], v[182:183], v[180:181]
	v_mov_b32_e32 v182, v87
	v_mov_b32_e32 v183, v83
	v_pk_add_f32 v[178:179], v[178:179], v[180:181]
	v_mov_b32_e32 v180, v86
	v_mov_b32_e32 v181, v82
	v_pk_mul_f32 v[182:183], v[182:183], v[182:183]
	v_mov_b32_e32 v185, v127
	v_pk_fma_f32 v[180:181], v[180:181], v[180:181], v[182:183]
	v_mov_b32_e32 v182, v88
	v_mov_b32_e32 v183, v84
	v_pk_fma_f32 v[180:181], v[182:183], v[182:183], v[180:181]
	v_mov_b32_e32 v182, v89
	v_mov_b32_e32 v183, v85
	v_pk_fma_f32 v[180:181], v[182:183], v[182:183], v[180:181]
	v_mov_b32_e32 v182, v71
	v_mov_b32_e32 v183, v67
	v_pk_add_f32 v[178:179], v[178:179], v[180:181]
	v_mov_b32_e32 v180, v70
	v_mov_b32_e32 v181, v66
	v_pk_mul_f32 v[182:183], v[182:183], v[182:183]
	v_pk_mul_f32 v[184:185], v[184:185], v[184:185]
	v_pk_fma_f32 v[180:181], v[180:181], v[180:181], v[182:183]
	v_mov_b32_e32 v182, v72
	v_mov_b32_e32 v183, v68
	v_pk_fma_f32 v[180:181], v[182:183], v[182:183], v[180:181]
	v_mov_b32_e32 v182, v73
	v_mov_b32_e32 v183, v69
	v_pk_fma_f32 v[180:181], v[182:183], v[182:183], v[180:181]
	v_mov_b32_e32 v182, v23
	v_pk_add_f32 v[178:179], v[178:179], v[180:181]
	v_mov_b32_e32 v180, v176
	v_mov_b32_e32 v181, v160
	v_mov_b32_e32 v183, v7
	v_pk_add_f32 v[178:179], v[178:179], v[180:181]
	v_mov_b32_e32 v180, v22
	v_mov_b32_e32 v181, v6
	v_pk_mul_f32 v[182:183], v[182:183], v[182:183]
	v_mov_b32_e32 v160, v177
	v_pk_fma_f32 v[180:181], v[180:181], v[180:181], v[182:183]
	v_mov_b32_e32 v182, v24
	v_mov_b32_e32 v183, v8
	v_pk_fma_f32 v[180:181], v[182:183], v[182:183], v[180:181]
	v_mov_b32_e32 v182, v25
	v_mov_b32_e32 v183, v9
	v_pk_fma_f32 v[180:181], v[182:183], v[182:183], v[180:181]
	v_pk_add_f32 v[160:161], v[178:179], v[160:161]
	v_mov_b32_e32 v176, v180
	v_mov_b32_e32 v177, v174
	v_pk_add_f32 v[160:161], v[160:161], v[176:177]
	v_mov_b32_e32 v174, v181
	v_pk_add_f32 v[160:161], v[160:161], v[174:175]
	ds_bpermute_b32 v175, v137, v161
	ds_bpermute_b32 v174, v137, v160
	v_mov_b32_e32 v178, v59
	v_mov_b32_e32 v179, v43
	v_pk_mul_f32 v[178:179], v[178:179], v[178:179]
	v_mov_b32_e32 v180, v27
	s_waitcnt lgkmcnt(0)
	v_pk_add_f32 v[160:161], v[160:161], v[174:175]
	ds_bpermute_b32 v175, v165, v161
	ds_bpermute_b32 v174, v165, v160
	v_mov_b32_e32 v181, v11
	v_pk_mul_f32 v[180:181], v[180:181], v[180:181]
	s_waitcnt vmcnt(3)
	v_mov_b32_e32 v182, v63
	s_waitcnt vmcnt(2)
	v_mov_b32_e32 v183, v47
	s_waitcnt lgkmcnt(0)
	v_pk_add_f32 v[160:161], v[160:161], v[174:175]
	ds_bpermute_b32 v175, v170, v161
	ds_bpermute_b32 v174, v170, v160
	v_pk_mul_f32 v[182:183], v[182:183], v[182:183]
	v_mov_b32_e32 v186, v111
	v_mov_b32_e32 v187, v107
	v_pk_mul_f32 v[186:187], v[186:187], v[186:187]
	s_waitcnt lgkmcnt(0)
	v_pk_add_f32 v[160:161], v[160:161], v[174:175]
	ds_bpermute_b32 v175, v171, v161
	ds_bpermute_b32 v174, v171, v160
	s_waitcnt lgkmcnt(0)
	v_pk_add_f32 v[160:161], v[160:161], v[174:175]
	ds_bpermute_b32 v175, v172, v161
	ds_bpermute_b32 v174, v172, v160
	s_waitcnt lgkmcnt(0)
	v_pk_add_f32 v[160:161], v[160:161], v[174:175]
	ds_bpermute_b32 v175, v173, v161
	ds_bpermute_b32 v174, v173, v160
	s_waitcnt lgkmcnt(0)
	v_pk_add_f32 v[160:161], v[160:161], v[174:175]
	v_mov_b64_e32 v[174:175], s[18:19]
	v_pk_fma_f32 v[176:177], v[160:161], s[16:17], v[174:175] op_sel_hi:[1,0,0]
	s_nop 0
	v_mul_f32_e32 v0, 0x4b800000, v177
	v_cmp_gt_f32_e64 s[46:47], s95, v177
	v_cmp_gt_f32_e32 vcc, s95, v176
	s_nop 0
	v_cndmask_b32_e64 v0, v177, v0, s[46:47]
	v_rsq_f32_e32 v0, v0
	v_mov_b32_e32 v177, v42
	v_mul_f32_e32 v131, 0x45800000, v0
	v_cndmask_b32_e64 v160, v0, v131, s[46:47]
	v_mul_f32_e32 v0, 0x4b800000, v176
	v_cndmask_b32_e32 v0, v176, v0, vcc
	v_mov_b32_e32 v176, v58
	v_pk_fma_f32 v[176:177], v[176:177], v[176:177], v[178:179]
	v_mov_b32_e32 v178, v60
	v_mov_b32_e32 v179, v44
	v_pk_fma_f32 v[176:177], v[178:179], v[178:179], v[176:177]
	v_mov_b32_e32 v178, v61
	v_mov_b32_e32 v179, v45
	v_pk_fma_f32 v[176:177], v[178:179], v[178:179], v[176:177]
	v_mov_b32_e32 v178, v26
	v_mov_b32_e32 v179, v10
	v_pk_fma_f32 v[178:179], v[178:179], v[178:179], v[180:181]
	v_mov_b32_e32 v180, v28
	v_mov_b32_e32 v181, v12
	v_pk_fma_f32 v[178:179], v[180:181], v[180:181], v[178:179]
	v_mov_b32_e32 v180, v29
	v_mov_b32_e32 v181, v13
	v_pk_fma_f32 v[178:179], v[180:181], v[180:181], v[178:179]
	v_mov_b32_e32 v180, v62
	v_mov_b32_e32 v181, v46
	v_pk_fma_f32 v[180:181], v[180:181], v[180:181], v[182:183]
	v_mov_b32_e32 v182, v64
	v_mov_b32_e32 v183, v48
	v_pk_fma_f32 v[180:181], v[182:183], v[182:183], v[180:181]
	v_mov_b32_e32 v182, v65
	v_mov_b32_e32 v183, v49
	v_pk_fma_f32 v[180:181], v[182:183], v[182:183], v[180:181]
	v_mov_b32_e32 v182, v118
	v_mov_b32_e32 v183, v126
	v_pk_fma_f32 v[182:183], v[182:183], v[182:183], v[184:185]
	v_mov_b32_e32 v184, v120
	v_mov_b32_e32 v185, v128
	v_pk_fma_f32 v[182:183], v[184:185], v[184:185], v[182:183]
	v_mov_b32_e32 v184, v121
	v_mov_b32_e32 v185, v129
	v_pk_fma_f32 v[182:183], v[184:185], v[184:185], v[182:183]
	v_mov_b32_e32 v184, v110
	v_mov_b32_e32 v185, v106
	v_pk_fma_f32 v[184:185], v[184:185], v[184:185], v[186:187]
	v_mov_b32_e32 v186, v112
	v_mov_b32_e32 v187, v108
	v_pk_fma_f32 v[184:185], v[186:187], v[186:187], v[184:185]
	v_mov_b32_e32 v186, v113
	v_mov_b32_e32 v187, v109
	v_pk_fma_f32 v[184:185], v[186:187], v[186:187], v[184:185]
	v_mov_b32_e32 v186, v95
	v_mov_b32_e32 v187, v91
	v_pk_add_f32 v[182:183], v[182:183], v[184:185]
	v_mov_b32_e32 v184, v94
	v_mov_b32_e32 v185, v90
	v_pk_mul_f32 v[186:187], v[186:187], v[186:187]
	v_rsq_f32_e32 v0, v0
	v_pk_fma_f32 v[184:185], v[184:185], v[184:185], v[186:187]
	v_mov_b32_e32 v186, v96
	v_mov_b32_e32 v187, v92
	v_pk_fma_f32 v[184:185], v[186:187], v[186:187], v[184:185]
	v_mov_b32_e32 v186, v97
	v_mov_b32_e32 v187, v93
	v_pk_fma_f32 v[184:185], v[186:187], v[186:187], v[184:185]
	v_mov_b32_e32 v186, v79
	v_mov_b32_e32 v187, v75
	v_pk_add_f32 v[182:183], v[182:183], v[184:185]
	v_mov_b32_e32 v184, v78
	v_mov_b32_e32 v185, v74
	v_pk_mul_f32 v[186:187], v[186:187], v[186:187]
	v_mul_f32_e32 v131, 0x45800000, v0
	v_pk_fma_f32 v[184:185], v[184:185], v[184:185], v[186:187]
	v_mov_b32_e32 v186, v80
	v_mov_b32_e32 v187, v76
	v_pk_fma_f32 v[184:185], v[186:187], v[186:187], v[184:185]
	v_mov_b32_e32 v186, v81
	v_mov_b32_e32 v187, v77
	v_pk_fma_f32 v[184:185], v[186:187], v[186:187], v[184:185]
	s_waitcnt vmcnt(1)
; __device__ __forceinline__ float* loutp(const Params& P) { return P.out + lzero(); }
; DI unsigned pk2(float lo, float hi) { const f32x2 v = {lo, hi}; return __builtin_bit_cast(unsigned, __builtin_convertvector(v, bf16n2)); }
; DI void phase_rmsnorm(LAS unsigned char* lds_, const Params& P, const float* gain, int mode, int fix, int nch) {
;     ...
;         for (int u = 0; u < 4; ++u) { float s = 0.f;
; #pragma unroll
;             for (int i = 0; i < 8; ++i) s += v4[u][i][0] * v4[u][i][0] + v4[u][i][1] * v4[u][i][1] + v4[u][i][2] * v4[u][i][2] + v4[u][i][3] * v4[u][i][3];
;             s4[u] = rsqrtf(wsum(s) * (1.f / DM) + 1e-6f); }
; #pragma unroll
;         for (int i = 0; i < 8; ++i) { const f32x4 g = *(const f32x4*)(gain + i * 256 + lane * 4);
; #pragma unroll
;             for (int u = 0; u < 4; ++u) { const size_t o = (size_t)(row + u * stride) * DM + i * 256 + lane * 4; const f32x4 ov = v4[u][i] * g * s4[u];
;                 if (mode == 2) *(f32x4*)(loutp(P) + O_Y + o) = ov;
;                 else { u32x2 w; w.x = pk2(ov[0], ov[1]); w.y = pk2(ov[2], ov[3]); *(u32x2*)(A16 + o) = w; }
	v_mov_b32_e32 v186, v31
	v_pk_add_f32 v[182:183], v[182:183], v[184:185]
	v_mov_b32_e32 v184, v180
	v_mov_b32_e32 v185, v176
	s_waitcnt vmcnt(0)
	v_mov_b32_e32 v187, v19
	v_pk_add_f32 v[182:183], v[182:183], v[184:185]
	v_mov_b32_e32 v184, v30
	v_mov_b32_e32 v185, v18
	v_pk_mul_f32 v[186:187], v[186:187], v[186:187]
	v_mov_b32_e32 v176, v181
	v_pk_fma_f32 v[184:185], v[184:185], v[184:185], v[186:187]
	v_mov_b32_e32 v186, v32
	v_mov_b32_e32 v187, v20
	v_pk_fma_f32 v[184:185], v[186:187], v[186:187], v[184:185]
	v_mov_b32_e32 v186, v33
	v_mov_b32_e32 v187, v21
	v_pk_fma_f32 v[184:185], v[186:187], v[186:187], v[184:185]
	v_pk_add_f32 v[176:177], v[182:183], v[176:177]
	v_mov_b32_e32 v180, v184
	v_mov_b32_e32 v181, v178
	v_pk_add_f32 v[176:177], v[176:177], v[180:181]
	v_mov_b32_e32 v178, v185
	v_pk_add_f32 v[176:177], v[176:177], v[178:179]
	ds_bpermute_b32 v179, v137, v177
	ds_bpermute_b32 v178, v137, v176
	v_cndmask_b32_e32 v0, v0, v131, vcc
	s_waitcnt lgkmcnt(0)
	v_pk_add_f32 v[176:177], v[176:177], v[178:179]
	ds_bpermute_b32 v179, v165, v177
	ds_bpermute_b32 v178, v165, v176
	s_waitcnt lgkmcnt(0)
	v_pk_add_f32 v[176:177], v[176:177], v[178:179]
	ds_bpermute_b32 v179, v170, v177
	ds_bpermute_b32 v178, v170, v176
	s_waitcnt lgkmcnt(0)
	v_pk_add_f32 v[176:177], v[176:177], v[178:179]
	ds_bpermute_b32 v179, v171, v177
	ds_bpermute_b32 v178, v171, v176
	s_waitcnt lgkmcnt(0)
	v_pk_add_f32 v[176:177], v[176:177], v[178:179]
	ds_bpermute_b32 v179, v172, v177
	ds_bpermute_b32 v178, v172, v176
	s_waitcnt lgkmcnt(0)
	v_pk_add_f32 v[176:177], v[176:177], v[178:179]
	ds_bpermute_b32 v179, v173, v177
	ds_bpermute_b32 v178, v173, v176
	s_waitcnt lgkmcnt(0)
	v_pk_add_f32 v[176:177], v[176:177], v[178:179]
	s_nop 0
	v_pk_fma_f32 v[174:175], v[176:177], s[16:17], v[174:175] op_sel_hi:[1,0,0]
	s_nop 0
	v_mul_f32_e32 v131, 0x4b800000, v175
	v_cmp_gt_f32_e64 s[46:47], s95, v175
	v_cmp_gt_f32_e32 vcc, s95, v174
	s_nop 0
	v_cndmask_b32_e64 v131, v175, v131, s[46:47]
	v_rsq_f32_e32 v131, v131
	s_nop 0
	v_mul_f32_e32 v133, 0x45800000, v131
	v_cndmask_b32_e64 v164, v131, v133, s[46:47]
	v_mul_f32_e32 v131, 0x4b800000, v174
	v_cndmask_b32_e32 v131, v174, v131, vcc
	v_rsq_f32_e32 v131, v131
	v_mov_b32_e32 v174, v206
	v_mov_b32_e32 v175, v207
	v_mov_b32_e32 v176, v208
	v_mov_b32_e32 v177, v209
	v_pk_mul_f32 v[116:117], v[116:117], v[176:177]
	s_nop 0
	v_pk_mul_f32 v[116:117], v[160:161], v[116:117] op_sel_hi:[0,1]
	v_pk_mul_f32 v[114:115], v[114:115], v[174:175]
	v_cvt_pk_bf16_f32 v179, v116, v117
	v_pk_mul_f32 v[116:117], v[124:125], v[176:177]
	v_pk_mul_f32 v[122:123], v[122:123], v[174:175]
	v_pk_mul_f32 v[114:115], v[160:161], v[114:115] op_sel_hi:[0,1]
	v_pk_mul_f32 v[116:117], v[0:1], v[116:117] op_sel_hi:[0,1]
	v_pk_mul_f32 v[122:123], v[0:1], v[122:123] op_sel_hi:[0,1]
	v_cvt_pk_bf16_f32 v178, v114, v115
	v_lshl_add_u64 v[114:115], s[92:93], 0, v[154:155]
	v_cvt_pk_bf16_f32 v122, v122, v123
	v_cvt_pk_bf16_f32 v123, v116, v117
	v_lshl_add_u64 v[116:117], s[92:93], 0, v[156:157]
	global_store_dwordx2 v[114:115], v[178:179], off
	global_store_dwordx2 v[116:117], v[122:123], off
	v_pk_mul_f32 v[122:123], v[128:129], v[176:177]
	v_pk_mul_f32 v[124:125], v[126:127], v[174:175]
	v_mul_f32_e32 v133, 0x45800000, v131
	v_pk_mul_f32 v[122:123], v[122:123], v[164:165] op_sel_hi:[1,0]
	v_pk_mul_f32 v[124:125], v[124:125], v[164:165] op_sel_hi:[1,0]
	v_cndmask_b32_e32 v162, v131, v133, vcc
	v_cvt_pk_bf16_f32 v124, v124, v125
	v_cvt_pk_bf16_f32 v125, v122, v123
	v_lshlrev_b64 v[122:123], 12, v[166:167]
	v_pk_mul_f32 v[118:119], v[118:119], v[174:175]
	v_lshl_add_u64 v[122:123], v[150:151], 0, v[122:123]
	v_pk_mul_f32 v[120:121], v[120:121], v[176:177]
	v_pk_mul_f32 v[118:119], v[118:119], v[162:163] op_sel_hi:[1,0]
	global_store_dwordx2 v[122:123], v[124:125], off
	v_pk_mul_f32 v[124:125], v[120:121], v[162:163] op_sel_hi:[1,0]
	v_cvt_pk_bf16_f32 v120, v118, v119
	v_lshlrev_b64 v[118:119], 12, v[168:169]
	v_cvt_pk_bf16_f32 v121, v124, v125
	v_lshl_add_u64 v[118:119], v[150:151], 0, v[118:119]
	global_store_dwordx2 v[118:119], v[120:121], off
	v_lshl_add_u64 v[154:155], v[154:155], 0, s[10:11]
	v_lshl_add_u64 v[156:157], v[156:157], 0, s[10:11]
	v_mov_b32_e32 v124, v210
	v_mov_b32_e32 v125, v211
	v_mov_b32_e32 v126, v212
	v_mov_b32_e32 v127, v213
	v_pk_mul_f32 v[100:101], v[100:101], v[126:127]
	v_pk_mul_f32 v[98:99], v[98:99], v[124:125]
	v_pk_mul_f32 v[100:101], v[160:161], v[100:101] op_sel_hi:[0,1]
	v_pk_mul_f32 v[98:99], v[160:161], v[98:99] op_sel_hi:[0,1]
	v_cvt_pk_bf16_f32 v98, v98, v99
	v_cvt_pk_bf16_f32 v99, v100, v101
	global_store_dwordx2 v[114:115], v[98:99], off offset:512
	v_pk_mul_f32 v[98:99], v[104:105], v[126:127]
	v_pk_mul_f32 v[100:101], v[102:103], v[124:125]
	v_pk_mul_f32 v[98:99], v[0:1], v[98:99] op_sel_hi:[0,1]
	v_pk_mul_f32 v[100:101], v[0:1], v[100:101] op_sel_hi:[0,1]
	v_cvt_pk_bf16_f32 v100, v100, v101
	v_cvt_pk_bf16_f32 v101, v98, v99
	global_store_dwordx2 v[116:117], v[100:101], off offset:512
	v_pk_mul_f32 v[98:99], v[108:109], v[126:127]
	v_pk_mul_f32 v[100:101], v[106:107], v[124:125]
	v_pk_mul_f32 v[98:99], v[164:165], v[98:99] op_sel_hi:[0,1]
	v_pk_mul_f32 v[100:101], v[164:165], v[100:101] op_sel_hi:[0,1]
	v_cvt_pk_bf16_f32 v100, v100, v101
	v_cvt_pk_bf16_f32 v101, v98, v99
	global_store_dwordx2 v[122:123], v[100:101], off offset:512
	v_pk_mul_f32 v[98:99], v[112:113], v[126:127]
	v_pk_mul_f32 v[100:101], v[110:111], v[124:125]
	v_pk_mul_f32 v[98:99], v[98:99], v[162:163] op_sel_hi:[1,0]
	v_pk_mul_f32 v[100:101], v[100:101], v[162:163] op_sel_hi:[1,0]
	s_nop 0
	v_cvt_pk_bf16_f32 v100, v100, v101
	v_cvt_pk_bf16_f32 v101, v98, v99
; __device__ __forceinline__ float* loutp(const Params& P) { return P.out + lzero(); }
; DI unsigned pk2(float lo, float hi) { const f32x2 v = {lo, hi}; return __builtin_bit_cast(unsigned, __builtin_convertvector(v, bf16n2)); }
; DI void phase_rmsnorm(LAS unsigned char* lds_, const Params& P, const float* gain, int mode, int fix, int nch) {
;     ...
;         for (int i = 0; i < 8; ++i) { const f32x4 g = *(const f32x4*)(gain + i * 256 + lane * 4);
; #pragma unroll
;             for (int u = 0; u < 4; ++u) { const size_t o = (size_t)(row + u * stride) * DM + i * 256 + lane * 4; const f32x4 ov = v4[u][i] * g * s4[u];
;                 if (mode == 2) *(f32x4*)(loutp(P) + O_Y + o) = ov;
;                 else { u32x2 w; w.x = pk2(ov[0], ov[1]); w.y = pk2(ov[2], ov[3]); *(u32x2*)(A16 + o) = w; }
	global_store_dwordx2 v[118:119], v[100:101], off offset:512
	v_mov_b32_e32 v98, v214
	v_mov_b32_e32 v99, v215
	v_mov_b32_e32 v100, v216
	v_mov_b32_e32 v101, v217
	v_pk_mul_f32 v[84:85], v[84:85], v[100:101]
	v_pk_mul_f32 v[82:83], v[82:83], v[98:99]
	v_pk_mul_f32 v[84:85], v[160:161], v[84:85] op_sel_hi:[0,1]
	v_pk_mul_f32 v[82:83], v[160:161], v[82:83] op_sel_hi:[0,1]
	v_cvt_pk_bf16_f32 v82, v82, v83
	v_cvt_pk_bf16_f32 v83, v84, v85
	global_store_dwordx2 v[114:115], v[82:83], off offset:1024
	v_pk_mul_f32 v[82:83], v[88:89], v[100:101]
	v_pk_mul_f32 v[84:85], v[86:87], v[98:99]
	v_pk_mul_f32 v[82:83], v[0:1], v[82:83] op_sel_hi:[0,1]
	v_pk_mul_f32 v[84:85], v[0:1], v[84:85] op_sel_hi:[0,1]
	v_cvt_pk_bf16_f32 v84, v84, v85
	v_cvt_pk_bf16_f32 v85, v82, v83
	global_store_dwordx2 v[116:117], v[84:85], off offset:1024
	v_pk_mul_f32 v[82:83], v[92:93], v[100:101]
	v_pk_mul_f32 v[84:85], v[90:91], v[98:99]
	v_pk_mul_f32 v[82:83], v[164:165], v[82:83] op_sel_hi:[0,1]
	v_pk_mul_f32 v[84:85], v[164:165], v[84:85] op_sel_hi:[0,1]
	v_cvt_pk_bf16_f32 v84, v84, v85
	v_cvt_pk_bf16_f32 v85, v82, v83
	global_store_dwordx2 v[122:123], v[84:85], off offset:1024
	v_pk_mul_f32 v[82:83], v[96:97], v[100:101]
	v_pk_mul_f32 v[84:85], v[94:95], v[98:99]
	v_pk_mul_f32 v[82:83], v[162:163], v[82:83] op_sel_hi:[0,1]
	v_pk_mul_f32 v[84:85], v[162:163], v[84:85] op_sel_hi:[0,1]
	v_cvt_pk_bf16_f32 v84, v84, v85
	v_cvt_pk_bf16_f32 v85, v82, v83
	global_store_dwordx2 v[118:119], v[84:85], off offset:1024
	v_mov_b32_e32 v82, v218
	v_mov_b32_e32 v83, v219
	v_mov_b32_e32 v84, v220
	v_mov_b32_e32 v85, v221
	v_pk_mul_f32 v[68:69], v[68:69], v[84:85]
	v_pk_mul_f32 v[66:67], v[66:67], v[82:83]
	v_pk_mul_f32 v[68:69], v[160:161], v[68:69] op_sel_hi:[0,1]
	v_pk_mul_f32 v[66:67], v[160:161], v[66:67] op_sel_hi:[0,1]
	v_cvt_pk_bf16_f32 v66, v66, v67
	v_cvt_pk_bf16_f32 v67, v68, v69
	global_store_dwordx2 v[114:115], v[66:67], off offset:1536
	v_pk_mul_f32 v[66:67], v[72:73], v[84:85]
	v_pk_mul_f32 v[68:69], v[70:71], v[82:83]
	v_pk_mul_f32 v[66:67], v[0:1], v[66:67] op_sel_hi:[0,1]
	v_pk_mul_f32 v[68:69], v[0:1], v[68:69] op_sel_hi:[0,1]
	v_cvt_pk_bf16_f32 v68, v68, v69
	v_cvt_pk_bf16_f32 v69, v66, v67
	global_store_dwordx2 v[116:117], v[68:69], off offset:1536
	v_pk_mul_f32 v[66:67], v[76:77], v[84:85]
	v_pk_mul_f32 v[68:69], v[74:75], v[82:83]
	v_pk_mul_f32 v[66:67], v[164:165], v[66:67] op_sel_hi:[0,1]
	v_pk_mul_f32 v[68:69], v[164:165], v[68:69] op_sel_hi:[0,1]
	v_cvt_pk_bf16_f32 v68, v68, v69
	v_cvt_pk_bf16_f32 v69, v66, v67
	global_store_dwordx2 v[122:123], v[68:69], off offset:1536
	v_pk_mul_f32 v[66:67], v[80:81], v[84:85]
	v_pk_mul_f32 v[68:69], v[78:79], v[82:83]
	v_pk_mul_f32 v[66:67], v[162:163], v[66:67] op_sel_hi:[0,1]
	v_pk_mul_f32 v[68:69], v[162:163], v[68:69] op_sel_hi:[0,1]
	v_cvt_pk_bf16_f32 v68, v68, v69
	v_cvt_pk_bf16_f32 v69, v66, v67
	global_store_dwordx2 v[118:119], v[68:69], off offset:1536
	v_mov_b32_e32 v66, v222
	v_mov_b32_e32 v67, v223
	v_mov_b32_e32 v68, v224
	v_mov_b32_e32 v69, v225
	v_pk_mul_f32 v[52:53], v[52:53], v[68:69]
	v_pk_mul_f32 v[50:51], v[50:51], v[66:67]
	v_pk_mul_f32 v[52:53], v[160:161], v[52:53] op_sel_hi:[0,1]
	v_pk_mul_f32 v[50:51], v[160:161], v[50:51] op_sel_hi:[0,1]
	v_cvt_pk_bf16_f32 v50, v50, v51
	v_cvt_pk_bf16_f32 v51, v52, v53
	global_store_dwordx2 v[114:115], v[50:51], off offset:2048
	v_pk_mul_f32 v[50:51], v[56:57], v[68:69]
	v_pk_mul_f32 v[52:53], v[54:55], v[66:67]
	v_pk_mul_f32 v[50:51], v[0:1], v[50:51] op_sel_hi:[0,1]
	v_pk_mul_f32 v[52:53], v[0:1], v[52:53] op_sel_hi:[0,1]
	v_cvt_pk_bf16_f32 v52, v52, v53
	v_cvt_pk_bf16_f32 v53, v50, v51
	global_store_dwordx2 v[116:117], v[52:53], off offset:2048
	v_pk_mul_f32 v[50:51], v[60:61], v[68:69]
	v_pk_mul_f32 v[52:53], v[58:59], v[66:67]
	v_pk_mul_f32 v[50:51], v[164:165], v[50:51] op_sel_hi:[0,1]
	v_pk_mul_f32 v[52:53], v[164:165], v[52:53] op_sel_hi:[0,1]
	v_cvt_pk_bf16_f32 v52, v52, v53
	v_cvt_pk_bf16_f32 v53, v50, v51
	global_store_dwordx2 v[122:123], v[52:53], off offset:2048
	v_pk_mul_f32 v[50:51], v[64:65], v[68:69]
	v_pk_mul_f32 v[52:53], v[62:63], v[66:67]
	v_pk_mul_f32 v[50:51], v[162:163], v[50:51] op_sel_hi:[0,1]
	v_pk_mul_f32 v[52:53], v[162:163], v[52:53] op_sel_hi:[0,1]
	v_cvt_pk_bf16_f32 v52, v52, v53
	v_cvt_pk_bf16_f32 v53, v50, v51
	global_store_dwordx2 v[118:119], v[52:53], off offset:2048
	v_mov_b32_e32 v50, v226
; __device__ __forceinline__ float* loutp(const Params& P) { return P.out + lzero(); }
; DI unsigned pk2(float lo, float hi) { const f32x2 v = {lo, hi}; return __builtin_bit_cast(unsigned, __builtin_convertvector(v, bf16n2)); }
; DI void phase_rmsnorm(LAS unsigned char* lds_, const Params& P, const float* gain, int mode, int fix, int nch) {
;     ...
;         for (int i = 0; i < 8; ++i) { const f32x4 g = *(const f32x4*)(gain + i * 256 + lane * 4);
; #pragma unroll
;             for (int u = 0; u < 4; ++u) { const size_t o = (size_t)(row + u * stride) * DM + i * 256 + lane * 4; const f32x4 ov = v4[u][i] * g * s4[u];
;                 if (mode == 2) *(f32x4*)(loutp(P) + O_Y + o) = ov;
;                 else { u32x2 w; w.x = pk2(ov[0], ov[1]); w.y = pk2(ov[2], ov[3]); *(u32x2*)(A16 + o) = w; }
;                 if (mode == 1) *(f32x4*)(H + o) = v4[u][i]; } }
;     }
	v_mov_b32_e32 v51, v227
	v_mov_b32_e32 v52, v228
	v_mov_b32_e32 v53, v229
	v_pk_mul_f32 v[36:37], v[36:37], v[52:53]
	v_pk_mul_f32 v[34:35], v[34:35], v[50:51]
	v_pk_mul_f32 v[36:37], v[160:161], v[36:37] op_sel_hi:[0,1]
	v_pk_mul_f32 v[34:35], v[160:161], v[34:35] op_sel_hi:[0,1]
	v_cvt_pk_bf16_f32 v34, v34, v35
	v_cvt_pk_bf16_f32 v35, v36, v37
	global_store_dwordx2 v[114:115], v[34:35], off offset:2560
	v_pk_mul_f32 v[34:35], v[40:41], v[52:53]
	v_pk_mul_f32 v[36:37], v[38:39], v[50:51]
	v_pk_mul_f32 v[34:35], v[0:1], v[34:35] op_sel_hi:[0,1]
	v_pk_mul_f32 v[36:37], v[0:1], v[36:37] op_sel_hi:[0,1]
	v_cvt_pk_bf16_f32 v36, v36, v37
	v_cvt_pk_bf16_f32 v37, v34, v35
	global_store_dwordx2 v[116:117], v[36:37], off offset:2560
	v_pk_mul_f32 v[34:35], v[44:45], v[52:53]
	v_pk_mul_f32 v[36:37], v[42:43], v[50:51]
	v_pk_mul_f32 v[34:35], v[164:165], v[34:35] op_sel_hi:[0,1]
	v_pk_mul_f32 v[36:37], v[164:165], v[36:37] op_sel_hi:[0,1]
	v_cvt_pk_bf16_f32 v36, v36, v37
	v_cvt_pk_bf16_f32 v37, v34, v35
	global_store_dwordx2 v[122:123], v[36:37], off offset:2560
	v_pk_mul_f32 v[34:35], v[48:49], v[52:53]
	v_pk_mul_f32 v[36:37], v[46:47], v[50:51]
	v_pk_mul_f32 v[34:35], v[162:163], v[34:35] op_sel_hi:[0,1]
	v_pk_mul_f32 v[36:37], v[162:163], v[36:37] op_sel_hi:[0,1]
	v_cvt_pk_bf16_f32 v36, v36, v37
	v_cvt_pk_bf16_f32 v37, v34, v35
	global_store_dwordx2 v[118:119], v[36:37], off offset:2560
	v_mov_b32_e32 v34, v230
	v_mov_b32_e32 v35, v231
	v_mov_b32_e32 v36, v232
	v_mov_b32_e32 v37, v233
	v_pk_mul_f32 v[16:17], v[16:17], v[36:37]
	v_pk_mul_f32 v[14:15], v[14:15], v[34:35]
	v_pk_mul_f32 v[16:17], v[160:161], v[16:17] op_sel_hi:[0,1]
	v_pk_mul_f32 v[14:15], v[160:161], v[14:15] op_sel_hi:[0,1]
	v_cvt_pk_bf16_f32 v14, v14, v15
	v_cvt_pk_bf16_f32 v15, v16, v17
	global_store_dwordx2 v[114:115], v[14:15], off offset:3072
	v_pk_mul_f32 v[14:15], v[24:25], v[36:37]
	v_pk_mul_f32 v[16:17], v[22:23], v[34:35]
	v_pk_mul_f32 v[14:15], v[0:1], v[14:15] op_sel_hi:[0,1]
	v_pk_mul_f32 v[16:17], v[0:1], v[16:17] op_sel_hi:[0,1]
	v_cvt_pk_bf16_f32 v16, v16, v17
	v_cvt_pk_bf16_f32 v17, v14, v15
	global_store_dwordx2 v[116:117], v[16:17], off offset:3072
	v_pk_mul_f32 v[14:15], v[28:29], v[36:37]
	v_pk_mul_f32 v[16:17], v[26:27], v[34:35]
	v_pk_mul_f32 v[14:15], v[164:165], v[14:15] op_sel_hi:[0,1]
	v_pk_mul_f32 v[16:17], v[164:165], v[16:17] op_sel_hi:[0,1]
	v_cvt_pk_bf16_f32 v16, v16, v17
	v_cvt_pk_bf16_f32 v17, v14, v15
	global_store_dwordx2 v[122:123], v[16:17], off offset:3072
	v_pk_mul_f32 v[14:15], v[32:33], v[36:37]
	v_pk_mul_f32 v[16:17], v[30:31], v[34:35]
	v_pk_mul_f32 v[14:15], v[162:163], v[14:15] op_sel_hi:[0,1]
	v_pk_mul_f32 v[16:17], v[162:163], v[16:17] op_sel_hi:[0,1]
	v_cvt_pk_bf16_f32 v16, v16, v17
	v_cvt_pk_bf16_f32 v17, v14, v15
	global_store_dwordx2 v[118:119], v[16:17], off offset:3072
	v_mov_b32_e32 v14, v188
	v_mov_b32_e32 v15, v189
	v_mov_b32_e32 v16, v190
	v_mov_b32_e32 v17, v191
	v_pk_mul_f32 v[4:5], v[4:5], v[16:17]
	v_pk_mul_f32 v[2:3], v[2:3], v[14:15]
	v_pk_mul_f32 v[4:5], v[160:161], v[4:5] op_sel_hi:[0,1]
	v_pk_mul_f32 v[2:3], v[160:161], v[2:3] op_sel_hi:[0,1]
	v_cvt_pk_bf16_f32 v2, v2, v3
	v_cvt_pk_bf16_f32 v3, v4, v5
	global_store_dwordx2 v[114:115], v[2:3], off offset:3584
	v_pk_mul_f32 v[2:3], v[8:9], v[16:17]
	v_pk_mul_f32 v[4:5], v[6:7], v[14:15]
	v_pk_mul_f32 v[2:3], v[0:1], v[2:3] op_sel_hi:[0,1]
	v_pk_mul_f32 v[4:5], v[0:1], v[4:5] op_sel_hi:[0,1]
	v_cvt_pk_bf16_f32 v4, v4, v5
	v_cvt_pk_bf16_f32 v5, v2, v3
	global_store_dwordx2 v[116:117], v[4:5], off offset:3584
	v_pk_mul_f32 v[2:3], v[12:13], v[16:17]
	v_pk_mul_f32 v[4:5], v[10:11], v[14:15]
	v_pk_mul_f32 v[2:3], v[164:165], v[2:3] op_sel_hi:[0,1]
	v_pk_mul_f32 v[4:5], v[164:165], v[4:5] op_sel_hi:[0,1]
	v_cvt_pk_bf16_f32 v4, v4, v5
	v_cvt_pk_bf16_f32 v5, v2, v3
	global_store_dwordx2 v[122:123], v[4:5], off offset:3584
	v_pk_mul_f32 v[2:3], v[20:21], v[16:17]
	v_pk_mul_f32 v[4:5], v[18:19], v[14:15]
	v_add_u32_e32 v0, s5, v130
	v_pk_mul_f32 v[2:3], v[162:163], v[2:3] op_sel_hi:[0,1]
	v_pk_mul_f32 v[4:5], v[162:163], v[4:5] op_sel_hi:[0,1]
	v_cmp_lt_i32_e32 vcc, s7, v0
	v_cvt_pk_bf16_f32 v4, v4, v5
	v_cvt_pk_bf16_f32 v5, v2, v3
	s_or_b64 s[54:55], vcc, s[54:55]
	global_store_dwordx2 v[118:119], v[4:5], off offset:3584
	s_andn2_b64 exec, exec, s[54:55]
	s_cbranch_execnz .LBB0_1880
	s_or_b64 exec, exec, s[54:55]

; __device__ __forceinline__ const float* lin(const Params& P, int k) { return P.in[k] + lzero(); }
; DI void phase_rmsnorm(LAS unsigned char* lds_, const Params& P, const float* gain, int mode, int fix, int nch) {
;     ...
;     for (; row + 3 * stride < MPR; row += 4 * stride) {
;         f32x4 v4[4][8]; float s4[4];
; #pragma unroll
;         for (int u = 0; u < 4; ++u) { const int r = row + u * stride; const float* sp = (mode == 1) ? lin(P, 0) + (size_t)r * DM : H + (size_t)r * DM;
; #pragma unroll
;             for (int i = 0; i < 8; ++i) v4[u][i] = *(const f32x4*)(sp + i * 256 + lane * 4); }
; #pragma unroll
;         for (int u = 0; u < 4; ++u) { float s = 0.f;
; #pragma unroll
;             for (int i = 0; i < 8; ++i) s += v4[u][i][0] * v4[u][i][0] + v4[u][i][1] * v4[u][i][1] + v4[u][i][2] * v4[u][i][2] + v4[u][i][3] * v4[u][i][3];
;             s4[u] = rsqrtf(wsum(s) * (1.f / DM) + 1e-6f); }
; #pragma unroll
;         for (int i = 0; i < 8; ++i) { const f32x4 g = *(const f32x4*)(gain + i * 256 + lane * 4);
.LBB0_2179:
	v_lshl_add_u64 v[2:3], s[92:93], 0, v[152:153]
	global_load_dwordx4 v[114:117], v[2:3], off
	global_load_dwordx4 v[98:101], v[2:3], off offset:1024
	global_load_dwordx4 v[82:85], v[2:3], off offset:2048
	global_load_dwordx4 v[66:69], v[2:3], off offset:3072
	v_add_co_u32_e32 v2, vcc, 0x1000, v2
	v_lshl_add_u64 v[6:7], s[92:93], 0, v[158:159]
	s_nop 0
	v_addc_co_u32_e32 v3, vcc, 0, v3, vcc
	global_load_dwordx4 v[50:53], v[2:3], off
	global_load_dwordx4 v[34:37], v[2:3], off offset:1024
	global_load_dwordx4 v[14:17], v[2:3], off offset:2048
	s_nop 0
	global_load_dwordx4 v[2:5], v[2:3], off offset:3072
	s_nop 0
	global_load_dwordx4 v[122:125], v[6:7], off
	global_load_dwordx4 v[102:105], v[6:7], off offset:1024
	global_load_dwordx4 v[86:89], v[6:7], off offset:2048
	global_load_dwordx4 v[70:73], v[6:7], off offset:3072
	v_add_co_u32_e32 v6, vcc, 0x1000, v6
	v_add_u32_e32 v166, s4, v130
	s_nop 0
	v_addc_co_u32_e32 v7, vcc, 0, v7, vcc
	global_load_dwordx4 v[54:57], v[6:7], off
	global_load_dwordx4 v[38:41], v[6:7], off offset:1024
	global_load_dwordx4 v[22:25], v[6:7], off offset:2048
	s_nop 0
	global_load_dwordx4 v[6:9], v[6:7], off offset:3072
	v_ashrrev_i32_e32 v167, 31, v166
	v_lshlrev_b64 v[10:11], 13, v[166:167]
	v_lshl_add_u64 v[10:11], v[148:149], 0, v[10:11]
	global_load_dwordx4 v[126:129], v[10:11], off
	global_load_dwordx4 v[106:109], v[10:11], off offset:1024
	global_load_dwordx4 v[90:93], v[10:11], off offset:2048
	global_load_dwordx4 v[74:77], v[10:11], off offset:3072
	v_add_co_u32_e32 v10, vcc, s88, v10
	v_add_u32_e32 v168, s5, v130
	s_nop 0
	v_addc_co_u32_e32 v11, vcc, 0, v11, vcc
	global_load_dwordx4 v[58:61], v[10:11], off
	global_load_dwordx4 v[42:45], v[10:11], off offset:1024
	global_load_dwordx4 v[26:29], v[10:11], off offset:2048
	s_nop 0
	global_load_dwordx4 v[10:13], v[10:11], off offset:3072
	v_ashrrev_i32_e32 v169, 31, v168
	v_lshlrev_b64 v[18:19], 13, v[168:169]
	v_lshl_add_u64 v[18:19], v[148:149], 0, v[18:19]
	global_load_dwordx4 v[118:121], v[18:19], off
	global_load_dwordx4 v[110:113], v[18:19], off offset:1024
	global_load_dwordx4 v[94:97], v[18:19], off offset:2048
	global_load_dwordx4 v[78:81], v[18:19], off offset:3072
	v_add_co_u32_e32 v18, vcc, s88, v18
	v_add_u32_e32 v130, s6, v130
	s_nop 0
	v_addc_co_u32_e32 v19, vcc, 0, v19, vcc
	global_load_dwordx4 v[62:65], v[18:19], off
	global_load_dwordx4 v[46:49], v[18:19], off offset:1024
	global_load_dwordx4 v[30:33], v[18:19], off offset:2048
	s_nop 0
	global_load_dwordx4 v[18:21], v[18:19], off offset:3072
	v_lshl_add_u64 v[152:153], v[152:153], 0, s[8:9]
	v_lshl_add_u64 v[158:159], v[158:159], 0, s[8:9]
	global_load_dwordx4 v[206:209], v[138:139], off
	global_load_dwordx4 v[210:213], v[138:139], off offset:1024
	global_load_dwordx4 v[214:217], v[138:139], off offset:2048
	global_load_dwordx4 v[218:221], v[138:139], off offset:3072
	global_load_dwordx4 v[222:225], v[140:141], off
	global_load_dwordx4 v[226:229], v[142:143], off
	global_load_dwordx4 v[230:233], v[144:145], off
	global_load_dwordx4 v[188:191], v[146:147], off
	s_waitcnt vmcnt(31)
	v_mov_b32_e32 v181, v115
	s_waitcnt vmcnt(30)
	v_mov_b32_e32 v183, v99
	s_waitcnt vmcnt(27)
	v_mov_b32_e32 v174, v51
	s_waitcnt vmcnt(26)
	v_mov_b32_e32 v175, v35
	v_mov_b32_e32 v160, v50
	v_mov_b32_e32 v161, v34
	v_pk_mul_f32 v[174:175], v[174:175], v[174:175]
	s_waitcnt vmcnt(25)
	v_mov_b32_e32 v176, v15
	v_pk_fma_f32 v[160:161], v[160:161], v[160:161], v[174:175]
	v_mov_b32_e32 v174, v52
	v_mov_b32_e32 v175, v36
	v_pk_fma_f32 v[160:161], v[174:175], v[174:175], v[160:161]
	v_mov_b32_e32 v174, v53
	v_mov_b32_e32 v175, v37
	s_waitcnt vmcnt(24)
	v_mov_b32_e32 v177, v3
	v_pk_fma_f32 v[160:161], v[174:175], v[174:175], v[160:161]
	v_mov_b32_e32 v174, v14
	v_mov_b32_e32 v175, v2
	v_pk_mul_f32 v[176:177], v[176:177], v[176:177]
	s_waitcnt vmcnt(19)
	v_mov_b32_e32 v178, v55
	v_pk_fma_f32 v[174:175], v[174:175], v[174:175], v[176:177]
	v_mov_b32_e32 v176, v16
	v_mov_b32_e32 v177, v4
	v_pk_fma_f32 v[174:175], v[176:177], v[176:177], v[174:175]
	v_mov_b32_e32 v176, v17
	v_mov_b32_e32 v177, v5
	s_waitcnt vmcnt(18)
	v_mov_b32_e32 v179, v39
	v_pk_fma_f32 v[174:175], v[176:177], v[176:177], v[174:175]
	v_mov_b32_e32 v176, v54
	v_mov_b32_e32 v177, v38
	v_pk_mul_f32 v[178:179], v[178:179], v[178:179]
	v_mov_b32_e32 v180, v123
	v_pk_fma_f32 v[176:177], v[176:177], v[176:177], v[178:179]
	v_mov_b32_e32 v178, v56
	v_mov_b32_e32 v179, v40
	v_pk_fma_f32 v[176:177], v[178:179], v[178:179], v[176:177]
	v_mov_b32_e32 v178, v57
	v_mov_b32_e32 v179, v41
	v_pk_fma_f32 v[176:177], v[178:179], v[178:179], v[176:177]
	v_mov_b32_e32 v178, v122
	v_mov_b32_e32 v179, v114
	v_pk_mul_f32 v[180:181], v[180:181], v[180:181]
	v_mov_b32_e32 v182, v103
	v_pk_fma_f32 v[178:179], v[178:179], v[178:179], v[180:181]
	v_mov_b32_e32 v180, v124
	v_mov_b32_e32 v181, v116
	v_pk_fma_f32 v[178:179], v[180:181], v[180:181], v[178:179]
	v_mov_b32_e32 v180, v125
	v_mov_b32_e32 v181, v117
	v_pk_fma_f32 v[178:179], v[180:181], v[180:181], v[178:179]
	v_mov_b32_e32 v180, v102
	v_mov_b32_e32 v181, v98
	v_pk_mul_f32 v[182:183], v[182:183], v[182:183]
	s_waitcnt vmcnt(7)
; DI void phase_rmsnorm(LAS unsigned char* lds_, const Params& P, const float* gain, int mode, int fix, int nch) {
;     ...
;         for (int u = 0; u < 4; ++u) { float s = 0.f;
; #pragma unroll
;             for (int i = 0; i < 8; ++i) s += v4[u][i][0] * v4[u][i][0] + v4[u][i][1] * v4[u][i][1] + v4[u][i][2] * v4[u][i][2] + v4[u][i][3] * v4[u][i][3];
;             s4[u] = rsqrtf(wsum(s) * (1.f / DM) + 1e-6f); }
	v_mov_b32_e32 v184, v119
	v_pk_fma_f32 v[180:181], v[180:181], v[180:181], v[182:183]
	v_mov_b32_e32 v182, v104
	v_mov_b32_e32 v183, v100
	v_pk_fma_f32 v[180:181], v[182:183], v[182:183], v[180:181]
	v_mov_b32_e32 v182, v105
	v_mov_b32_e32 v183, v101
	v_pk_fma_f32 v[180:181], v[182:183], v[182:183], v[180:181]
	v_mov_b32_e32 v182, v87
	v_mov_b32_e32 v183, v83
	v_pk_add_f32 v[178:179], v[178:179], v[180:181]
	v_mov_b32_e32 v180, v86
	v_mov_b32_e32 v181, v82
	v_pk_mul_f32 v[182:183], v[182:183], v[182:183]
	v_mov_b32_e32 v185, v127
	v_pk_fma_f32 v[180:181], v[180:181], v[180:181], v[182:183]
	v_mov_b32_e32 v182, v88
	v_mov_b32_e32 v183, v84
	v_pk_fma_f32 v[180:181], v[182:183], v[182:183], v[180:181]
	v_mov_b32_e32 v182, v89
	v_mov_b32_e32 v183, v85
	v_pk_fma_f32 v[180:181], v[182:183], v[182:183], v[180:181]
	v_mov_b32_e32 v182, v71
	v_mov_b32_e32 v183, v67
	v_pk_add_f32 v[178:179], v[178:179], v[180:181]
	v_mov_b32_e32 v180, v70
	v_mov_b32_e32 v181, v66
	v_pk_mul_f32 v[182:183], v[182:183], v[182:183]
	v_pk_mul_f32 v[184:185], v[184:185], v[184:185]
	v_pk_fma_f32 v[180:181], v[180:181], v[180:181], v[182:183]
	v_mov_b32_e32 v182, v72
	v_mov_b32_e32 v183, v68
	v_pk_fma_f32 v[180:181], v[182:183], v[182:183], v[180:181]
	v_mov_b32_e32 v182, v73
	v_mov_b32_e32 v183, v69
	v_pk_fma_f32 v[180:181], v[182:183], v[182:183], v[180:181]
	v_mov_b32_e32 v182, v23
	v_pk_add_f32 v[178:179], v[178:179], v[180:181]
	v_mov_b32_e32 v180, v176
	v_mov_b32_e32 v181, v160
	v_mov_b32_e32 v183, v7
	v_pk_add_f32 v[178:179], v[178:179], v[180:181]
	v_mov_b32_e32 v180, v22
	v_mov_b32_e32 v181, v6
	v_pk_mul_f32 v[182:183], v[182:183], v[182:183]
	v_mov_b32_e32 v160, v177
	v_pk_fma_f32 v[180:181], v[180:181], v[180:181], v[182:183]
	v_mov_b32_e32 v182, v24
	v_mov_b32_e32 v183, v8
	v_pk_fma_f32 v[180:181], v[182:183], v[182:183], v[180:181]
	v_mov_b32_e32 v182, v25
	v_mov_b32_e32 v183, v9
	v_pk_fma_f32 v[180:181], v[182:183], v[182:183], v[180:181]
	v_pk_add_f32 v[160:161], v[178:179], v[160:161]
	v_mov_b32_e32 v176, v180
	v_mov_b32_e32 v177, v174
	v_pk_add_f32 v[160:161], v[160:161], v[176:177]
	v_mov_b32_e32 v174, v181
	v_pk_add_f32 v[160:161], v[160:161], v[174:175]
	ds_bpermute_b32 v175, v137, v161
	ds_bpermute_b32 v174, v137, v160
	v_mov_b32_e32 v178, v59
	v_mov_b32_e32 v179, v43
	v_pk_mul_f32 v[178:179], v[178:179], v[178:179]
	v_mov_b32_e32 v180, v27
	s_waitcnt lgkmcnt(0)
	v_pk_add_f32 v[160:161], v[160:161], v[174:175]
	ds_bpermute_b32 v175, v165, v161
	ds_bpermute_b32 v174, v165, v160
	v_mov_b32_e32 v181, v11
	v_pk_mul_f32 v[180:181], v[180:181], v[180:181]
	s_waitcnt vmcnt(3)
	v_mov_b32_e32 v182, v63
	s_waitcnt vmcnt(2)
	v_mov_b32_e32 v183, v47
	s_waitcnt lgkmcnt(0)
	v_pk_add_f32 v[160:161], v[160:161], v[174:175]
	ds_bpermute_b32 v175, v170, v161
	ds_bpermute_b32 v174, v170, v160
	v_pk_mul_f32 v[182:183], v[182:183], v[182:183]
	v_mov_b32_e32 v186, v111
	v_mov_b32_e32 v187, v107
	v_pk_mul_f32 v[186:187], v[186:187], v[186:187]
	s_waitcnt lgkmcnt(0)
	v_pk_add_f32 v[160:161], v[160:161], v[174:175]
	ds_bpermute_b32 v175, v171, v161
	ds_bpermute_b32 v174, v171, v160
	s_waitcnt lgkmcnt(0)
	v_pk_add_f32 v[160:161], v[160:161], v[174:175]
	ds_bpermute_b32 v175, v172, v161
	ds_bpermute_b32 v174, v172, v160
	s_waitcnt lgkmcnt(0)
	v_pk_add_f32 v[160:161], v[160:161], v[174:175]
	ds_bpermute_b32 v175, v173, v161
	ds_bpermute_b32 v174, v173, v160
	s_waitcnt lgkmcnt(0)
	v_pk_add_f32 v[160:161], v[160:161], v[174:175]
	v_mov_b64_e32 v[174:175], s[12:13]
	v_pk_fma_f32 v[176:177], v[160:161], s[10:11], v[174:175] op_sel_hi:[1,0,0]
	s_nop 0
	v_mul_f32_e32 v0, 0x4b800000, v177
	v_cmp_gt_f32_e64 s[44:45], s95, v177
	v_cmp_gt_f32_e32 vcc, s95, v176
	s_nop 0
	v_cndmask_b32_e64 v0, v177, v0, s[44:45]
	v_rsq_f32_e32 v0, v0
	v_mov_b32_e32 v177, v42
	v_mul_f32_e32 v131, 0x45800000, v0
	v_cndmask_b32_e64 v160, v0, v131, s[44:45]
	v_mul_f32_e32 v0, 0x4b800000, v176
	v_cndmask_b32_e32 v0, v176, v0, vcc
	v_mov_b32_e32 v176, v58
	v_pk_fma_f32 v[176:177], v[176:177], v[176:177], v[178:179]
	v_mov_b32_e32 v178, v60
	v_mov_b32_e32 v179, v44
	v_pk_fma_f32 v[176:177], v[178:179], v[178:179], v[176:177]
	v_mov_b32_e32 v178, v61
	v_mov_b32_e32 v179, v45
	v_pk_fma_f32 v[176:177], v[178:179], v[178:179], v[176:177]
	v_mov_b32_e32 v178, v26
	v_mov_b32_e32 v179, v10
	v_pk_fma_f32 v[178:179], v[178:179], v[178:179], v[180:181]
	v_mov_b32_e32 v180, v28
	v_mov_b32_e32 v181, v12
	v_pk_fma_f32 v[178:179], v[180:181], v[180:181], v[178:179]
	v_mov_b32_e32 v180, v29
	v_mov_b32_e32 v181, v13
	v_pk_fma_f32 v[178:179], v[180:181], v[180:181], v[178:179]
	v_mov_b32_e32 v180, v62
	v_mov_b32_e32 v181, v46
	v_pk_fma_f32 v[180:181], v[180:181], v[180:181], v[182:183]
	v_mov_b32_e32 v182, v64
	v_mov_b32_e32 v183, v48
	v_pk_fma_f32 v[180:181], v[182:183], v[182:183], v[180:181]
	v_mov_b32_e32 v182, v65
	v_mov_b32_e32 v183, v49
	v_pk_fma_f32 v[180:181], v[182:183], v[182:183], v[180:181]
	v_mov_b32_e32 v182, v118
	v_mov_b32_e32 v183, v126
	v_pk_fma_f32 v[182:183], v[182:183], v[182:183], v[184:185]
	v_mov_b32_e32 v184, v120
	v_mov_b32_e32 v185, v128
	v_pk_fma_f32 v[182:183], v[184:185], v[184:185], v[182:183]
	v_mov_b32_e32 v184, v121
	v_mov_b32_e32 v185, v129
	v_pk_fma_f32 v[182:183], v[184:185], v[184:185], v[182:183]
	v_mov_b32_e32 v184, v110
	v_mov_b32_e32 v185, v106
	v_pk_fma_f32 v[184:185], v[184:185], v[184:185], v[186:187]
	v_mov_b32_e32 v186, v112
	v_mov_b32_e32 v187, v108
	v_pk_fma_f32 v[184:185], v[186:187], v[186:187], v[184:185]
	v_mov_b32_e32 v186, v113
	v_mov_b32_e32 v187, v109
	v_pk_fma_f32 v[184:185], v[186:187], v[186:187], v[184:185]
	v_mov_b32_e32 v186, v95
	v_mov_b32_e32 v187, v91
	v_pk_add_f32 v[182:183], v[182:183], v[184:185]
	v_mov_b32_e32 v184, v94
	v_mov_b32_e32 v185, v90
	v_pk_mul_f32 v[186:187], v[186:187], v[186:187]
	v_rsq_f32_e32 v0, v0
	v_pk_fma_f32 v[184:185], v[184:185], v[184:185], v[186:187]
	v_mov_b32_e32 v186, v96
	v_mov_b32_e32 v187, v92
	v_pk_fma_f32 v[184:185], v[186:187], v[186:187], v[184:185]
	v_mov_b32_e32 v186, v97
	v_mov_b32_e32 v187, v93
	v_pk_fma_f32 v[184:185], v[186:187], v[186:187], v[184:185]
	v_mov_b32_e32 v186, v79
	v_mov_b32_e32 v187, v75
	v_pk_add_f32 v[182:183], v[182:183], v[184:185]
	v_mov_b32_e32 v184, v78
	v_mov_b32_e32 v185, v74
	v_pk_mul_f32 v[186:187], v[186:187], v[186:187]
	v_mul_f32_e32 v131, 0x45800000, v0
	v_pk_fma_f32 v[184:185], v[184:185], v[184:185], v[186:187]
	v_mov_b32_e32 v186, v80
	v_mov_b32_e32 v187, v76
	v_pk_fma_f32 v[184:185], v[186:187], v[186:187], v[184:185]
	v_mov_b32_e32 v186, v81
	v_mov_b32_e32 v187, v77
	v_pk_fma_f32 v[184:185], v[186:187], v[186:187], v[184:185]
	s_waitcnt vmcnt(1)
; __device__ __forceinline__ float* loutp(const Params& P) { return P.out + lzero(); }
; DI unsigned pk2(float lo, float hi) { const f32x2 v = {lo, hi}; return __builtin_bit_cast(unsigned, __builtin_convertvector(v, bf16n2)); }
; DI void phase_rmsnorm(LAS unsigned char* lds_, const Params& P, const float* gain, int mode, int fix, int nch) {
;     ...
;         for (int u = 0; u < 4; ++u) { float s = 0.f;
; #pragma unroll
;             for (int i = 0; i < 8; ++i) s += v4[u][i][0] * v4[u][i][0] + v4[u][i][1] * v4[u][i][1] + v4[u][i][2] * v4[u][i][2] + v4[u][i][3] * v4[u][i][3];
;             s4[u] = rsqrtf(wsum(s) * (1.f / DM) + 1e-6f); }
; #pragma unroll
;         for (int i = 0; i < 8; ++i) { const f32x4 g = *(const f32x4*)(gain + i * 256 + lane * 4);
; #pragma unroll
;             for (int u = 0; u < 4; ++u) { const size_t o = (size_t)(row + u * stride) * DM + i * 256 + lane * 4; const f32x4 ov = v4[u][i] * g * s4[u];
;                 if (mode == 2) *(f32x4*)(loutp(P) + O_Y + o) = ov;
;                 else { u32x2 w; w.x = pk2(ov[0], ov[1]); w.y = pk2(ov[2], ov[3]); *(u32x2*)(A16 + o) = w; }
	v_mov_b32_e32 v186, v31
	v_pk_add_f32 v[182:183], v[182:183], v[184:185]
	v_mov_b32_e32 v184, v180
	v_mov_b32_e32 v185, v176
	s_waitcnt vmcnt(0)
	v_mov_b32_e32 v187, v19
	v_pk_add_f32 v[182:183], v[182:183], v[184:185]
	v_mov_b32_e32 v184, v30
	v_mov_b32_e32 v185, v18
	v_pk_mul_f32 v[186:187], v[186:187], v[186:187]
	v_mov_b32_e32 v176, v181
	v_pk_fma_f32 v[184:185], v[184:185], v[184:185], v[186:187]
	v_mov_b32_e32 v186, v32
	v_mov_b32_e32 v187, v20
	v_pk_fma_f32 v[184:185], v[186:187], v[186:187], v[184:185]
	v_mov_b32_e32 v186, v33
	v_mov_b32_e32 v187, v21
	v_pk_fma_f32 v[184:185], v[186:187], v[186:187], v[184:185]
	v_pk_add_f32 v[176:177], v[182:183], v[176:177]
	v_mov_b32_e32 v180, v184
	v_mov_b32_e32 v181, v178
	v_pk_add_f32 v[176:177], v[176:177], v[180:181]
	v_mov_b32_e32 v178, v185
	v_pk_add_f32 v[176:177], v[176:177], v[178:179]
	ds_bpermute_b32 v179, v137, v177
	ds_bpermute_b32 v178, v137, v176
	v_cndmask_b32_e32 v0, v0, v131, vcc
	s_waitcnt lgkmcnt(0)
	v_pk_add_f32 v[176:177], v[176:177], v[178:179]
	ds_bpermute_b32 v179, v165, v177
	ds_bpermute_b32 v178, v165, v176
	s_waitcnt lgkmcnt(0)
	v_pk_add_f32 v[176:177], v[176:177], v[178:179]
	ds_bpermute_b32 v179, v170, v177
	ds_bpermute_b32 v178, v170, v176
	s_waitcnt lgkmcnt(0)
	v_pk_add_f32 v[176:177], v[176:177], v[178:179]
	ds_bpermute_b32 v179, v171, v177
	ds_bpermute_b32 v178, v171, v176
	s_waitcnt lgkmcnt(0)
	v_pk_add_f32 v[176:177], v[176:177], v[178:179]
	ds_bpermute_b32 v179, v172, v177
	ds_bpermute_b32 v178, v172, v176
	s_waitcnt lgkmcnt(0)
	v_pk_add_f32 v[176:177], v[176:177], v[178:179]
	ds_bpermute_b32 v179, v173, v177
	ds_bpermute_b32 v178, v173, v176
	s_waitcnt lgkmcnt(0)
	v_pk_add_f32 v[176:177], v[176:177], v[178:179]
	s_nop 0
	v_pk_fma_f32 v[174:175], v[176:177], s[10:11], v[174:175] op_sel_hi:[1,0,0]
	s_nop 0
	v_mul_f32_e32 v131, 0x4b800000, v175
	v_cmp_gt_f32_e64 s[44:45], s95, v175
	v_cmp_gt_f32_e32 vcc, s95, v174
	s_nop 0
	v_cndmask_b32_e64 v131, v175, v131, s[44:45]
	v_rsq_f32_e32 v131, v131
	s_nop 0
	v_mul_f32_e32 v133, 0x45800000, v131
	v_cndmask_b32_e64 v164, v131, v133, s[44:45]
	v_mul_f32_e32 v131, 0x4b800000, v174
	v_cndmask_b32_e32 v131, v174, v131, vcc
	v_rsq_f32_e32 v131, v131
	v_mov_b32_e32 v174, v206
	v_mov_b32_e32 v175, v207
	v_mov_b32_e32 v176, v208
	v_mov_b32_e32 v177, v209
	v_pk_mul_f32 v[116:117], v[116:117], v[176:177]
	s_nop 0
	v_pk_mul_f32 v[116:117], v[160:161], v[116:117] op_sel_hi:[0,1]
	v_pk_mul_f32 v[114:115], v[114:115], v[174:175]
	v_cvt_pk_bf16_f32 v179, v116, v117
	v_pk_mul_f32 v[116:117], v[124:125], v[176:177]
	v_pk_mul_f32 v[122:123], v[122:123], v[174:175]
	v_pk_mul_f32 v[114:115], v[160:161], v[114:115] op_sel_hi:[0,1]
	v_pk_mul_f32 v[116:117], v[0:1], v[116:117] op_sel_hi:[0,1]
	v_pk_mul_f32 v[122:123], v[0:1], v[122:123] op_sel_hi:[0,1]
	v_cvt_pk_bf16_f32 v178, v114, v115
	v_lshl_add_u64 v[114:115], s[92:93], 0, v[154:155]
	v_cvt_pk_bf16_f32 v122, v122, v123
	v_cvt_pk_bf16_f32 v123, v116, v117
	v_lshl_add_u64 v[116:117], s[92:93], 0, v[156:157]
	global_store_dwordx2 v[114:115], v[178:179], off
	global_store_dwordx2 v[116:117], v[122:123], off
	v_pk_mul_f32 v[122:123], v[128:129], v[176:177]
	v_pk_mul_f32 v[124:125], v[126:127], v[174:175]
	v_mul_f32_e32 v133, 0x45800000, v131
	v_pk_mul_f32 v[122:123], v[122:123], v[164:165] op_sel_hi:[1,0]
	v_pk_mul_f32 v[124:125], v[124:125], v[164:165] op_sel_hi:[1,0]
	v_cndmask_b32_e32 v162, v131, v133, vcc
	v_cvt_pk_bf16_f32 v124, v124, v125
	v_cvt_pk_bf16_f32 v125, v122, v123
	v_lshlrev_b64 v[122:123], 12, v[166:167]
	v_pk_mul_f32 v[118:119], v[118:119], v[174:175]
	v_lshl_add_u64 v[122:123], v[150:151], 0, v[122:123]
	v_pk_mul_f32 v[120:121], v[120:121], v[176:177]
	v_pk_mul_f32 v[118:119], v[118:119], v[162:163] op_sel_hi:[1,0]
	global_store_dwordx2 v[122:123], v[124:125], off
	v_pk_mul_f32 v[124:125], v[120:121], v[162:163] op_sel_hi:[1,0]
	v_cvt_pk_bf16_f32 v120, v118, v119
	v_lshlrev_b64 v[118:119], 12, v[168:169]
	v_cvt_pk_bf16_f32 v121, v124, v125
	v_lshl_add_u64 v[118:119], v[150:151], 0, v[118:119]
	global_store_dwordx2 v[118:119], v[120:121], off
	v_lshl_add_u64 v[154:155], v[154:155], 0, s[14:15]
	v_lshl_add_u64 v[156:157], v[156:157], 0, s[14:15]
	v_mov_b32_e32 v124, v210
	v_mov_b32_e32 v125, v211
	v_mov_b32_e32 v126, v212
	v_mov_b32_e32 v127, v213
	v_pk_mul_f32 v[100:101], v[100:101], v[126:127]
	v_pk_mul_f32 v[98:99], v[98:99], v[124:125]
	v_pk_mul_f32 v[100:101], v[160:161], v[100:101] op_sel_hi:[0,1]
	v_pk_mul_f32 v[98:99], v[160:161], v[98:99] op_sel_hi:[0,1]
	v_cvt_pk_bf16_f32 v98, v98, v99
	v_cvt_pk_bf16_f32 v99, v100, v101
	global_store_dwordx2 v[114:115], v[98:99], off offset:512
	v_pk_mul_f32 v[98:99], v[104:105], v[126:127]
	v_pk_mul_f32 v[100:101], v[102:103], v[124:125]
	v_pk_mul_f32 v[98:99], v[0:1], v[98:99] op_sel_hi:[0,1]
	v_pk_mul_f32 v[100:101], v[0:1], v[100:101] op_sel_hi:[0,1]
	v_cvt_pk_bf16_f32 v100, v100, v101
	v_cvt_pk_bf16_f32 v101, v98, v99
	global_store_dwordx2 v[116:117], v[100:101], off offset:512
	v_pk_mul_f32 v[98:99], v[108:109], v[126:127]
	v_pk_mul_f32 v[100:101], v[106:107], v[124:125]
	v_pk_mul_f32 v[98:99], v[164:165], v[98:99] op_sel_hi:[0,1]
	v_pk_mul_f32 v[100:101], v[164:165], v[100:101] op_sel_hi:[0,1]
	v_cvt_pk_bf16_f32 v100, v100, v101
	v_cvt_pk_bf16_f32 v101, v98, v99
	global_store_dwordx2 v[122:123], v[100:101], off offset:512
	v_pk_mul_f32 v[98:99], v[112:113], v[126:127]
	v_pk_mul_f32 v[100:101], v[110:111], v[124:125]
	v_pk_mul_f32 v[98:99], v[98:99], v[162:163] op_sel_hi:[1,0]
	v_pk_mul_f32 v[100:101], v[100:101], v[162:163] op_sel_hi:[1,0]
	s_nop 0
	v_cvt_pk_bf16_f32 v100, v100, v101
	v_cvt_pk_bf16_f32 v101, v98, v99
; __device__ __forceinline__ float* loutp(const Params& P) { return P.out + lzero(); }
; DI unsigned pk2(float lo, float hi) { const f32x2 v = {lo, hi}; return __builtin_bit_cast(unsigned, __builtin_convertvector(v, bf16n2)); }
; DI void phase_rmsnorm(LAS unsigned char* lds_, const Params& P, const float* gain, int mode, int fix, int nch) {
;     ...
;         for (int i = 0; i < 8; ++i) { const f32x4 g = *(const f32x4*)(gain + i * 256 + lane * 4);
; #pragma unroll
;             for (int u = 0; u < 4; ++u) { const size_t o = (size_t)(row + u * stride) * DM + i * 256 + lane * 4; const f32x4 ov = v4[u][i] * g * s4[u];
;                 if (mode == 2) *(f32x4*)(loutp(P) + O_Y + o) = ov;
;                 else { u32x2 w; w.x = pk2(ov[0], ov[1]); w.y = pk2(ov[2], ov[3]); *(u32x2*)(A16 + o) = w; }
	global_store_dwordx2 v[118:119], v[100:101], off offset:512
	v_mov_b32_e32 v98, v214
	v_mov_b32_e32 v99, v215
	v_mov_b32_e32 v100, v216
	v_mov_b32_e32 v101, v217
	v_pk_mul_f32 v[84:85], v[84:85], v[100:101]
	v_pk_mul_f32 v[82:83], v[82:83], v[98:99]
	v_pk_mul_f32 v[84:85], v[160:161], v[84:85] op_sel_hi:[0,1]
	v_pk_mul_f32 v[82:83], v[160:161], v[82:83] op_sel_hi:[0,1]
	v_cvt_pk_bf16_f32 v82, v82, v83
	v_cvt_pk_bf16_f32 v83, v84, v85
	global_store_dwordx2 v[114:115], v[82:83], off offset:1024
	v_pk_mul_f32 v[82:83], v[88:89], v[100:101]
	v_pk_mul_f32 v[84:85], v[86:87], v[98:99]
	v_pk_mul_f32 v[82:83], v[0:1], v[82:83] op_sel_hi:[0,1]
	v_pk_mul_f32 v[84:85], v[0:1], v[84:85] op_sel_hi:[0,1]
	v_cvt_pk_bf16_f32 v84, v84, v85
	v_cvt_pk_bf16_f32 v85, v82, v83
	global_store_dwordx2 v[116:117], v[84:85], off offset:1024
	v_pk_mul_f32 v[82:83], v[92:93], v[100:101]
	v_pk_mul_f32 v[84:85], v[90:91], v[98:99]
	v_pk_mul_f32 v[82:83], v[164:165], v[82:83] op_sel_hi:[0,1]
	v_pk_mul_f32 v[84:85], v[164:165], v[84:85] op_sel_hi:[0,1]
	v_cvt_pk_bf16_f32 v84, v84, v85
	v_cvt_pk_bf16_f32 v85, v82, v83
	global_store_dwordx2 v[122:123], v[84:85], off offset:1024
	v_pk_mul_f32 v[82:83], v[96:97], v[100:101]
	v_pk_mul_f32 v[84:85], v[94:95], v[98:99]
	v_pk_mul_f32 v[82:83], v[162:163], v[82:83] op_sel_hi:[0,1]
	v_pk_mul_f32 v[84:85], v[162:163], v[84:85] op_sel_hi:[0,1]
	v_cvt_pk_bf16_f32 v84, v84, v85
	v_cvt_pk_bf16_f32 v85, v82, v83
	global_store_dwordx2 v[118:119], v[84:85], off offset:1024
	v_mov_b32_e32 v82, v218
	v_mov_b32_e32 v83, v219
	v_mov_b32_e32 v84, v220
	v_mov_b32_e32 v85, v221
	v_pk_mul_f32 v[68:69], v[68:69], v[84:85]
	v_pk_mul_f32 v[66:67], v[66:67], v[82:83]
	v_pk_mul_f32 v[68:69], v[160:161], v[68:69] op_sel_hi:[0,1]
	v_pk_mul_f32 v[66:67], v[160:161], v[66:67] op_sel_hi:[0,1]
	v_cvt_pk_bf16_f32 v66, v66, v67
	v_cvt_pk_bf16_f32 v67, v68, v69
	global_store_dwordx2 v[114:115], v[66:67], off offset:1536
	v_pk_mul_f32 v[66:67], v[72:73], v[84:85]
	v_pk_mul_f32 v[68:69], v[70:71], v[82:83]
	v_pk_mul_f32 v[66:67], v[0:1], v[66:67] op_sel_hi:[0,1]
	v_pk_mul_f32 v[68:69], v[0:1], v[68:69] op_sel_hi:[0,1]
	v_cvt_pk_bf16_f32 v68, v68, v69
	v_cvt_pk_bf16_f32 v69, v66, v67
	global_store_dwordx2 v[116:117], v[68:69], off offset:1536
	v_pk_mul_f32 v[66:67], v[76:77], v[84:85]
	v_pk_mul_f32 v[68:69], v[74:75], v[82:83]
	v_pk_mul_f32 v[66:67], v[164:165], v[66:67] op_sel_hi:[0,1]
	v_pk_mul_f32 v[68:69], v[164:165], v[68:69] op_sel_hi:[0,1]
	v_cvt_pk_bf16_f32 v68, v68, v69
	v_cvt_pk_bf16_f32 v69, v66, v67
	global_store_dwordx2 v[122:123], v[68:69], off offset:1536
	v_pk_mul_f32 v[66:67], v[80:81], v[84:85]
	v_pk_mul_f32 v[68:69], v[78:79], v[82:83]
	v_pk_mul_f32 v[66:67], v[162:163], v[66:67] op_sel_hi:[0,1]
	v_pk_mul_f32 v[68:69], v[162:163], v[68:69] op_sel_hi:[0,1]
	v_cvt_pk_bf16_f32 v68, v68, v69
	v_cvt_pk_bf16_f32 v69, v66, v67
	global_store_dwordx2 v[118:119], v[68:69], off offset:1536
	v_mov_b32_e32 v66, v222
	v_mov_b32_e32 v67, v223
	v_mov_b32_e32 v68, v224
	v_mov_b32_e32 v69, v225
	v_pk_mul_f32 v[52:53], v[52:53], v[68:69]
	v_pk_mul_f32 v[50:51], v[50:51], v[66:67]
	v_pk_mul_f32 v[52:53], v[160:161], v[52:53] op_sel_hi:[0,1]
	v_pk_mul_f32 v[50:51], v[160:161], v[50:51] op_sel_hi:[0,1]
	v_cvt_pk_bf16_f32 v50, v50, v51
	v_cvt_pk_bf16_f32 v51, v52, v53
	global_store_dwordx2 v[114:115], v[50:51], off offset:2048
	v_pk_mul_f32 v[50:51], v[56:57], v[68:69]
	v_pk_mul_f32 v[52:53], v[54:55], v[66:67]
	v_pk_mul_f32 v[50:51], v[0:1], v[50:51] op_sel_hi:[0,1]
	v_pk_mul_f32 v[52:53], v[0:1], v[52:53] op_sel_hi:[0,1]
	v_cvt_pk_bf16_f32 v52, v52, v53
	v_cvt_pk_bf16_f32 v53, v50, v51
	global_store_dwordx2 v[116:117], v[52:53], off offset:2048
	v_pk_mul_f32 v[50:51], v[60:61], v[68:69]
	v_pk_mul_f32 v[52:53], v[58:59], v[66:67]
	v_pk_mul_f32 v[50:51], v[164:165], v[50:51] op_sel_hi:[0,1]
	v_pk_mul_f32 v[52:53], v[164:165], v[52:53] op_sel_hi:[0,1]
	v_cvt_pk_bf16_f32 v52, v52, v53
	v_cvt_pk_bf16_f32 v53, v50, v51
	global_store_dwordx2 v[122:123], v[52:53], off offset:2048
	v_pk_mul_f32 v[50:51], v[64:65], v[68:69]
	v_pk_mul_f32 v[52:53], v[62:63], v[66:67]
	v_pk_mul_f32 v[50:51], v[162:163], v[50:51] op_sel_hi:[0,1]
	v_pk_mul_f32 v[52:53], v[162:163], v[52:53] op_sel_hi:[0,1]
	v_cvt_pk_bf16_f32 v52, v52, v53
	v_cvt_pk_bf16_f32 v53, v50, v51
	global_store_dwordx2 v[118:119], v[52:53], off offset:2048
	v_mov_b32_e32 v50, v226
; __device__ __forceinline__ float* loutp(const Params& P) { return P.out + lzero(); }
; DI unsigned pk2(float lo, float hi) { const f32x2 v = {lo, hi}; return __builtin_bit_cast(unsigned, __builtin_convertvector(v, bf16n2)); }
; DI void phase_rmsnorm(LAS unsigned char* lds_, const Params& P, const float* gain, int mode, int fix, int nch) {
;     ...
;         for (int i = 0; i < 8; ++i) { const f32x4 g = *(const f32x4*)(gain + i * 256 + lane * 4);
; #pragma unroll
;             for (int u = 0; u < 4; ++u) { const size_t o = (size_t)(row + u * stride) * DM + i * 256 + lane * 4; const f32x4 ov = v4[u][i] * g * s4[u];
;                 if (mode == 2) *(f32x4*)(loutp(P) + O_Y + o) = ov;
;                 else { u32x2 w; w.x = pk2(ov[0], ov[1]); w.y = pk2(ov[2], ov[3]); *(u32x2*)(A16 + o) = w; }
;                 if (mode == 1) *(f32x4*)(H + o) = v4[u][i]; } }
;     }
	v_mov_b32_e32 v51, v227
	v_mov_b32_e32 v52, v228
	v_mov_b32_e32 v53, v229
	v_pk_mul_f32 v[36:37], v[36:37], v[52:53]
	v_pk_mul_f32 v[34:35], v[34:35], v[50:51]
	v_pk_mul_f32 v[36:37], v[160:161], v[36:37] op_sel_hi:[0,1]
	v_pk_mul_f32 v[34:35], v[160:161], v[34:35] op_sel_hi:[0,1]
	v_cvt_pk_bf16_f32 v34, v34, v35
	v_cvt_pk_bf16_f32 v35, v36, v37
	global_store_dwordx2 v[114:115], v[34:35], off offset:2560
	v_pk_mul_f32 v[34:35], v[40:41], v[52:53]
	v_pk_mul_f32 v[36:37], v[38:39], v[50:51]
	v_pk_mul_f32 v[34:35], v[0:1], v[34:35] op_sel_hi:[0,1]
	v_pk_mul_f32 v[36:37], v[0:1], v[36:37] op_sel_hi:[0,1]
	v_cvt_pk_bf16_f32 v36, v36, v37
	v_cvt_pk_bf16_f32 v37, v34, v35
	global_store_dwordx2 v[116:117], v[36:37], off offset:2560
	v_pk_mul_f32 v[34:35], v[44:45], v[52:53]
	v_pk_mul_f32 v[36:37], v[42:43], v[50:51]
	v_pk_mul_f32 v[34:35], v[164:165], v[34:35] op_sel_hi:[0,1]
	v_pk_mul_f32 v[36:37], v[164:165], v[36:37] op_sel_hi:[0,1]
	v_cvt_pk_bf16_f32 v36, v36, v37
	v_cvt_pk_bf16_f32 v37, v34, v35
	global_store_dwordx2 v[122:123], v[36:37], off offset:2560
	v_pk_mul_f32 v[34:35], v[48:49], v[52:53]
	v_pk_mul_f32 v[36:37], v[46:47], v[50:51]
	v_pk_mul_f32 v[34:35], v[162:163], v[34:35] op_sel_hi:[0,1]
	v_pk_mul_f32 v[36:37], v[162:163], v[36:37] op_sel_hi:[0,1]
	v_cvt_pk_bf16_f32 v36, v36, v37
	v_cvt_pk_bf16_f32 v37, v34, v35
	global_store_dwordx2 v[118:119], v[36:37], off offset:2560
	v_mov_b32_e32 v34, v230
	v_mov_b32_e32 v35, v231
	v_mov_b32_e32 v36, v232
	v_mov_b32_e32 v37, v233
	v_pk_mul_f32 v[16:17], v[16:17], v[36:37]
	v_pk_mul_f32 v[14:15], v[14:15], v[34:35]
	v_pk_mul_f32 v[16:17], v[160:161], v[16:17] op_sel_hi:[0,1]
	v_pk_mul_f32 v[14:15], v[160:161], v[14:15] op_sel_hi:[0,1]
	v_cvt_pk_bf16_f32 v14, v14, v15
	v_cvt_pk_bf16_f32 v15, v16, v17
	global_store_dwordx2 v[114:115], v[14:15], off offset:3072
	v_pk_mul_f32 v[14:15], v[24:25], v[36:37]
	v_pk_mul_f32 v[16:17], v[22:23], v[34:35]
	v_pk_mul_f32 v[14:15], v[0:1], v[14:15] op_sel_hi:[0,1]
	v_pk_mul_f32 v[16:17], v[0:1], v[16:17] op_sel_hi:[0,1]
	v_cvt_pk_bf16_f32 v16, v16, v17
	v_cvt_pk_bf16_f32 v17, v14, v15
	global_store_dwordx2 v[116:117], v[16:17], off offset:3072
	v_pk_mul_f32 v[14:15], v[28:29], v[36:37]
	v_pk_mul_f32 v[16:17], v[26:27], v[34:35]
	v_pk_mul_f32 v[14:15], v[164:165], v[14:15] op_sel_hi:[0,1]
	v_pk_mul_f32 v[16:17], v[164:165], v[16:17] op_sel_hi:[0,1]
	v_cvt_pk_bf16_f32 v16, v16, v17
	v_cvt_pk_bf16_f32 v17, v14, v15
	global_store_dwordx2 v[122:123], v[16:17], off offset:3072
	v_pk_mul_f32 v[14:15], v[32:33], v[36:37]
	v_pk_mul_f32 v[16:17], v[30:31], v[34:35]
	v_pk_mul_f32 v[14:15], v[162:163], v[14:15] op_sel_hi:[0,1]
	v_pk_mul_f32 v[16:17], v[162:163], v[16:17] op_sel_hi:[0,1]
	v_cvt_pk_bf16_f32 v16, v16, v17
	v_cvt_pk_bf16_f32 v17, v14, v15
	global_store_dwordx2 v[118:119], v[16:17], off offset:3072
	v_mov_b32_e32 v14, v188
	v_mov_b32_e32 v15, v189
	v_mov_b32_e32 v16, v190
	v_mov_b32_e32 v17, v191
	v_pk_mul_f32 v[4:5], v[4:5], v[16:17]
	v_pk_mul_f32 v[2:3], v[2:3], v[14:15]
	v_pk_mul_f32 v[4:5], v[160:161], v[4:5] op_sel_hi:[0,1]
	v_pk_mul_f32 v[2:3], v[160:161], v[2:3] op_sel_hi:[0,1]
	v_cvt_pk_bf16_f32 v2, v2, v3
	v_cvt_pk_bf16_f32 v3, v4, v5
	global_store_dwordx2 v[114:115], v[2:3], off offset:3584
	v_pk_mul_f32 v[2:3], v[8:9], v[16:17]
	v_pk_mul_f32 v[4:5], v[6:7], v[14:15]
	v_pk_mul_f32 v[2:3], v[0:1], v[2:3] op_sel_hi:[0,1]
	v_pk_mul_f32 v[4:5], v[0:1], v[4:5] op_sel_hi:[0,1]
	v_cvt_pk_bf16_f32 v4, v4, v5
	v_cvt_pk_bf16_f32 v5, v2, v3
	global_store_dwordx2 v[116:117], v[4:5], off offset:3584
	v_pk_mul_f32 v[2:3], v[12:13], v[16:17]
	v_pk_mul_f32 v[4:5], v[10:11], v[14:15]
	v_pk_mul_f32 v[2:3], v[164:165], v[2:3] op_sel_hi:[0,1]
	v_pk_mul_f32 v[4:5], v[164:165], v[4:5] op_sel_hi:[0,1]
	v_cvt_pk_bf16_f32 v4, v4, v5
	v_cvt_pk_bf16_f32 v5, v2, v3
	global_store_dwordx2 v[122:123], v[4:5], off offset:3584
	v_pk_mul_f32 v[2:3], v[20:21], v[16:17]
	v_pk_mul_f32 v[4:5], v[18:19], v[14:15]
	v_add_u32_e32 v0, s5, v130
	v_pk_mul_f32 v[2:3], v[162:163], v[2:3] op_sel_hi:[0,1]
	v_pk_mul_f32 v[4:5], v[162:163], v[4:5] op_sel_hi:[0,1]
	v_cmp_lt_i32_e32 vcc, s7, v0
	v_cvt_pk_bf16_f32 v4, v4, v5
	v_cvt_pk_bf16_f32 v5, v2, v3
	s_or_b64 s[52:53], vcc, s[52:53]
	global_store_dwordx2 v[118:119], v[4:5], off offset:3584
	s_andn2_b64 exec, exec, s[52:53]
	s_cbranch_execnz .LBB0_2179
	s_or_b64 exec, exec, s[52:53]
